# attention: stage-interleaved LDS map, two stage-specialised tile bodies (no per-tile address VALU / stage toggles)
# baseline (speedup 1.0000x reference)
.LBB0_254:
	s_cmp_lt_i32 s59, 1
	s_cbranch_scc1 .LBB0_360
	s_add_u32 s3, s66, 0x20200000
	v_writelane_b32 v254, s90, 11
	s_addc_u32 s6, s67, 0
	s_ashr_i32 s0, s88, 4
	v_writelane_b32 v254, s91, 12
	s_and_b32 s0, s0, -2
	v_writelane_b32 v254, s0, 13
	v_writelane_b32 v254, s88, 14
	s_and_b32 s0, s88, 31
	v_writelane_b32 v254, s0, 15
	s_and_b32 s0, s87, 0xffffffc0
	v_mov_b32_e32 v0, 0x3e4ccccd
	v_writelane_b32 v254, s0, 16
	s_lshl_b32 s0, s0, 2
	v_add_f32_e32 v0, s1, v0
	s_add_i32 s96, s0, 0
	s_add_i32 s0, s89, -4
	s_lshl_b32 s1, s89, 7
	s_lshl_b32 s4, s89, 18
	s_bfe_u32 s7, s87, 0x20006
	s_lshl_b32 s9, s0, 17
	s_and_b32 s1, s1, 0xffffff00
	s_and_b32 s4, s4, 0x40000
	s_lshl_b32 s0, s0, 13
	s_lshr_b32 s8, s87, 8
	s_lshl_b32 s14, s7, 5
	s_add_i32 s96, s96, 0x20200
	s_add_i32 s10, s1, s4
	s_lshl_b32 s11, s89, 13
	s_add_i32 s12, s0, 0x10000
	s_cmpk_lt_u32 s87, 0x100
	s_cselect_b64 s[0:1], -1, 0
	s_and_b64 s[4:5], s[0:1], exec
	s_movk_i32 s5, 0x80
	v_writelane_b32 v254, s89, 17
	s_cselect_b32 s4, s11, s12
	s_cselect_b32 s11, 0x8000, s5
	s_mov_b32 s5, 0x10000
	v_writelane_b32 v254, s87, 18
	s_cselect_b32 s12, s5, 0x100
	s_mov_b32 s5, 0x18000
	s_cselect_b32 s20, 0xc0, 0
	s_cselect_b32 s16, s5, 0x180
	s_mov_b32 s5, 0x20000
	v_writelane_b32 v254, s20, 19
	s_cselect_b32 s20, 0x80, 0
	s_cselect_b32 s17, s5, 0x10000
	s_mov_b32 s5, 0x28000
	v_writelane_b32 v254, s20, 20
	s_cselect_b32 s20, 64, 0
	s_cselect_b32 s18, s5, 0x10080
	s_mov_b32 s5, 0x30000
	v_writelane_b32 v254, s20, 21
	s_cselect_b32 s19, s5, 0x10100
	s_mov_b32 s5, 0x38000
	s_cselect_b32 s63, s95, s6
	v_writelane_b32 v254, s94, 22
	s_cselect_b32 s5, s5, 0x10180
	s_cselect_b32 s93, s10, s9
	v_writelane_b32 v254, s95, 23
	s_cselect_b32 s62, s94, s3
	s_add_i32 s97, s4, 0
	s_lshl_b32 s4, s8, 14
	v_writelane_b32 v254, s4, 24
	s_lshl_b32 s4, s7, 15
	s_add_i32 s75, s97, 0x400
	s_add_i32 s68, s97, 0x800
	s_add_i32 s69, s97, 0xc00
	s_add_i32 s78, s97, 0x1000
	s_add_i32 s79, s97, 0x1400
	s_add_i32 s54, s97, 0x1800
	s_add_i32 s55, s97, 0x1c00
	s_lshl_b32 s3, s8, 7
	s_add_i32 s71, s97, 0x10000
	s_add_i32 s92, s97, 0x10400
	s_add_i32 s70, s97, 0x10800
	s_add_i32 s80, s97, 0x10c00
	s_add_i32 s81, s97, 0x11000
	s_add_i32 s50, s97, 0x11400
	s_add_i32 s51, s97, 0x11800
	s_add_i32 s94, s97, 0x11c00
	s_add_i32 s95, s4, 0
	s_cmp_eq_u32 s8, 1
	s_cselect_b64 s[6:7], -1, 0
	v_writelane_b32 v254, s6, 25
	s_lshl_b32 s4, s8, 4
	s_mov_b32 s15, 0
	v_writelane_b32 v254, s7, 26
	v_writelane_b32 v254, s4, 27
	v_writelane_b32 v254, s14, 28
	s_add_i32 s4, s14, 0xffffffa5
	v_writelane_b32 v254, s4, 29
	v_writelane_b32 v254, s5, 30
	s_add_i32 s4, s93, s5
	v_writelane_b32 v254, s4, 31
	v_writelane_b32 v254, s16, 32
	s_add_i32 s4, s93, s16
	v_writelane_b32 v254, s4, 33
	v_writelane_b32 v254, s19, 34
	s_add_i32 s4, s93, s19
	v_writelane_b32 v254, s4, 35
	v_writelane_b32 v254, s12, 36
	s_add_i32 s4, s93, s12
	v_writelane_b32 v254, s4, 37
	v_writelane_b32 v254, s18, 38
	s_add_i32 s4, s93, s18
	v_writelane_b32 v254, s4, 39
	v_writelane_b32 v254, s11, 40
	s_add_i32 s4, s93, s11
	v_writelane_b32 v254, s4, 41
	v_writelane_b32 v254, s17, 42
	s_add_i32 s4, s93, s17
	v_xor_b32_e32 v210, 0x80000000, v0
	v_writelane_b32 v254, s4, 43
	s_lshl_b32 s14, s3, 1
	v_mov_b32_e32 v212, v210
	v_mov_b32_e32 v213, v210
	v_mov_b32_e32 v1, 0
	s_mov_b32 s74, 0x41000000
	v_mov_b32_e32 v214, 0x3727c5ac
	v_mov_b32_e32 v215, 0x41b17218
	v_mov_b32_e32 v216, 0xff800000
	v_writelane_b32 v254, s14, 44
	s_mov_b32 s72, s15
	s_nop 0
	v_writelane_b32 v254, s15, 45
	s_branch .LBB0_257

.Lat_entry:
	s_mov_b32 s92, m0
	s_add_i32 s71, s97, 0x8000
	s_movk_i32 s81, 0x7f
	s_mov_b32 s80, 0x20000
	s_add_i32 s51, s90, 0x80000
	s_add_u32 s50, s62, s51
	s_addc_u32 s51, s63, 0
	s_mov_b32 s84, 1
	s_mov_b32 s94, 0xff800000
	v_mov_b32_e32 v246, 0
	v_mov_b32_e32 v247, 0
	v_mov_b32_e32 v248, 0
	v_mov_b32_e32 v249, 0
	v_mov_b32_e32 v250, 0
	v_mov_b32_e32 v251, 0
	v_mov_b32_e32 v252, 0
	v_mov_b32_e32 v253, 0
	v_readlane_b32 s4, v254, 24
	v_and_b32_e32 v234, 15, v211
	v_lshrrev_b32_e32 v235, 4, v211
	v_xor_b32_e32 v236, v234, v235
	v_lshlrev_b32_e32 v236, 4, v236
	v_lshl_add_u32 v236, v234, 8, v236
	v_add_u32_e32 v221, s4, v236
	v_lshlrev_b32_e32 v237, 2, v235
	v_sub_u32_e32 v237, v234, v237
	v_add_u32_e32 v223, s3, v237
	v_bfe_u32 v237, v211, 5, 1
	v_lshlrev_b32_e32 v237, 12, v237
	v_bfe_u32 v238, v211, 4, 1
	v_lshl_add_u32 v237, v238, 7, v237
	v_bfe_u32 v238, v211, 2, 2
	v_lshl_add_u32 v237, v238, 5, v237
	v_and_b32_e32 v238, 3, v211
	v_lshl_add_u32 v237, v238, 3, v237
	v_add_u32_e32 v242, 0x10000, v237
	v_mov_b32_e32 v244, 0
	v_mov_b32_e32 v234, v221
	v_xor_b32_e32 v235, 64, v234
	v_xor_b32_e32 v236, 0x80, v234
	v_xor_b32_e32 v237, 0xc0, v234
.Lat_loop:
	s_waitcnt vmcnt(0) lgkmcnt(0)
	s_barrier
	s_cmp_gt_u32 s58, s89
	s_cbranch_scc1 .Lat_inactive0
	ds_read_b128 v[162:165], v234
	ds_read_b128 v[166:169], v235
	ds_read_b128 v[170:173], v236
	ds_read_b128 v[174:177], v237
	s_add_i32 m0, s71, 0x0
	s_nop 0
	global_load_lds_dwordx4 v231, s[50:51]
	s_add_i32 m0, s71, 0x400
	s_nop 0
	global_load_lds_dwordx4 v229, s[50:51]
	s_waitcnt lgkmcnt(2)
	v_mfma_f32_16x16x32_bf16 v[130:133], v[162:165], v[178:181], v[246:249]
	v_mfma_f32_16x16x32_bf16 v[146:149], v[162:165], v[194:197], v[250:253]
	ds_read_b128 v[162:165], v234 offset:4096
	v_mfma_f32_16x16x32_bf16 v[130:133], v[166:169], v[182:185], v[130:133]
	s_add_i32 m0, s71, 0x800
	v_mfma_f32_16x16x32_bf16 v[146:149], v[166:169], v[198:201], v[146:149]
	ds_read_b128 v[166:169], v235 offset:4096
	global_load_lds_dwordx4 v227, s[50:51]
	s_waitcnt lgkmcnt(2)
	v_mfma_f32_16x16x32_bf16 v[130:133], v[170:173], v[186:189], v[130:133]
	v_mfma_f32_16x16x32_bf16 v[146:149], v[170:173], v[202:205], v[146:149]
	ds_read_b128 v[170:173], v236 offset:4096
	v_mfma_f32_16x16x32_bf16 v[130:133], v[174:177], v[190:193], v[130:133]
	s_add_i32 m0, s71, 0xc00
	v_mfma_f32_16x16x32_bf16 v[146:149], v[174:177], v[206:209], v[146:149]
	ds_read_b128 v[174:177], v237 offset:4096
	global_load_lds_dwordx4 v225, s[50:51]
	s_waitcnt lgkmcnt(2)
	v_mfma_f32_16x16x32_bf16 v[134:137], v[162:165], v[178:181], v[246:249]
	v_mfma_f32_16x16x32_bf16 v[150:153], v[162:165], v[194:197], v[250:253]
	ds_read_b128 v[162:165], v234 offset:8192
	v_mfma_f32_16x16x32_bf16 v[134:137], v[166:169], v[182:185], v[134:137]
	s_add_i32 m0, s71, 0x1000
	v_mfma_f32_16x16x32_bf16 v[150:153], v[166:169], v[198:201], v[150:153]
	ds_read_b128 v[166:169], v235 offset:8192
	global_load_lds_dwordx4 v230, s[50:51]
	s_waitcnt lgkmcnt(2)
	v_mfma_f32_16x16x32_bf16 v[134:137], v[170:173], v[186:189], v[134:137]
	v_mfma_f32_16x16x32_bf16 v[150:153], v[170:173], v[202:205], v[150:153]
	ds_read_b128 v[170:173], v236 offset:8192
	v_mfma_f32_16x16x32_bf16 v[134:137], v[174:177], v[190:193], v[134:137]
	s_add_i32 m0, s71, 0x1400
	v_mfma_f32_16x16x32_bf16 v[150:153], v[174:177], v[206:209], v[150:153]
	ds_read_b128 v[174:177], v237 offset:8192
	global_load_lds_dwordx4 v228, s[50:51]
	s_waitcnt lgkmcnt(2)
	v_mfma_f32_16x16x32_bf16 v[138:141], v[162:165], v[178:181], v[246:249]
	v_mfma_f32_16x16x32_bf16 v[154:157], v[162:165], v[194:197], v[250:253]
	ds_read_b128 v[162:165], v234 offset:12288
	v_mfma_f32_16x16x32_bf16 v[138:141], v[166:169], v[182:185], v[138:141]
	s_add_i32 m0, s71, 0x1800
	v_mfma_f32_16x16x32_bf16 v[154:157], v[166:169], v[198:201], v[154:157]
	ds_read_b128 v[166:169], v235 offset:12288
	global_load_lds_dwordx4 v226, s[50:51]
	s_waitcnt lgkmcnt(2)
	v_mfma_f32_16x16x32_bf16 v[138:141], v[170:173], v[186:189], v[138:141]
	v_mfma_f32_16x16x32_bf16 v[154:157], v[170:173], v[202:205], v[154:157]
	ds_read_b128 v[170:173], v236 offset:12288
	v_mfma_f32_16x16x32_bf16 v[138:141], v[174:177], v[190:193], v[138:141]
	s_add_i32 m0, s71, 0x1c00
	v_mfma_f32_16x16x32_bf16 v[154:157], v[174:177], v[206:209], v[154:157]
	ds_read_b128 v[174:177], v237 offset:12288
	global_load_lds_dwordx4 v224, s[50:51]
	s_waitcnt lgkmcnt(2)
	v_mfma_f32_16x16x32_bf16 v[142:145], v[162:165], v[178:181], v[246:249]
	v_mfma_f32_16x16x32_bf16 v[158:161], v[162:165], v[194:197], v[250:253]
	ds_read_b64_tr_b16 v[162:163], v242 offset:0
	ds_read_b64_tr_b16 v[164:165], v242 offset:8192
	v_mfma_f32_16x16x32_bf16 v[142:145], v[166:169], v[182:185], v[142:145]
	v_mfma_f32_16x16x32_bf16 v[158:161], v[166:169], v[198:201], v[158:161]
	ds_read_b64_tr_b16 v[166:167], v242 offset:16384
	ds_read_b64_tr_b16 v[168:169], v242 offset:24576
	s_waitcnt lgkmcnt(4)
	v_mfma_f32_16x16x32_bf16 v[142:145], v[170:173], v[186:189], v[142:145]
	v_mfma_f32_16x16x32_bf16 v[158:161], v[170:173], v[202:205], v[158:161]
	ds_read_b64_tr_b16 v[170:171], v242 offset:256
	ds_read_b64_tr_b16 v[172:173], v242 offset:8448
	v_mfma_f32_16x16x32_bf16 v[142:145], v[174:177], v[190:193], v[142:145]
	v_mfma_f32_16x16x32_bf16 v[158:161], v[174:177], v[206:209], v[158:161]
	ds_read_b64_tr_b16 v[174:175], v242 offset:16640
	ds_read_b64_tr_b16 v[176:177], v242 offset:24832

.Lat_exp_a:
	v_exp_f32_e32 v130, v130
	v_exp_f32_e32 v131, v131
	v_exp_f32_e32 v132, v132
	v_add_f32_e32 v0, v130, v131
	v_exp_f32_e32 v133, v133
	v_add_f32_e32 v0, v0, v132
	v_exp_f32_e32 v134, v134
	v_add_f32_e32 v0, v0, v133
	v_exp_f32_e32 v135, v135
	v_add_f32_e32 v0, v0, v134
	v_exp_f32_e32 v136, v136
	v_add_f32_e32 v0, v0, v135
	v_exp_f32_e32 v137, v137
	v_add_f32_e32 v0, v0, v136
	v_exp_f32_e32 v138, v138
	v_add_f32_e32 v0, v0, v137
	v_exp_f32_e32 v139, v139
	v_add_f32_e32 v0, v0, v138
	v_exp_f32_e32 v140, v140
	v_add_f32_e32 v0, v0, v139
	v_exp_f32_e32 v141, v141
	v_add_f32_e32 v0, v0, v140
	v_exp_f32_e32 v142, v142
	v_add_f32_e32 v0, v0, v141
	v_exp_f32_e32 v143, v143
	v_add_f32_e32 v0, v0, v142
	v_exp_f32_e32 v144, v144
	v_add_f32_e32 v0, v0, v143
	v_exp_f32_e32 v145, v145
	v_add_f32_e32 v0, v0, v144
	v_exp_f32_e32 v146, v146
	v_exp_f32_e32 v147, v147
	v_exp_f32_e32 v148, v148
	v_add_f32_e32 v233, v146, v147
	v_exp_f32_e32 v149, v149
	v_add_f32_e32 v233, v233, v148
	v_exp_f32_e32 v150, v150
	v_add_f32_e32 v233, v233, v149
	v_exp_f32_e32 v151, v151
	v_add_f32_e32 v233, v233, v150
	v_exp_f32_e32 v152, v152
	v_add_f32_e32 v233, v233, v151
	v_exp_f32_e32 v153, v153
	v_add_f32_e32 v233, v233, v152
	v_exp_f32_e32 v154, v154
	v_add_f32_e32 v233, v233, v153
	v_exp_f32_e32 v155, v155
	v_add_f32_e32 v233, v233, v154
	v_exp_f32_e32 v156, v156
	v_add_f32_e32 v233, v233, v155
	v_exp_f32_e32 v157, v157
	v_add_f32_e32 v233, v233, v156
	v_exp_f32_e32 v158, v158
	v_add_f32_e32 v233, v233, v157
	v_exp_f32_e32 v159, v159
	v_add_f32_e32 v233, v233, v158
	v_exp_f32_e32 v160, v160
	v_add_f32_e32 v233, v233, v159
	v_exp_f32_e32 v161, v161
	v_add_f32_e32 v233, v233, v160
	v_add_f32_e32 v0, v0, v145
	v_add_f32_e32 v233, v233, v161
	v_max_f32_e32 v238, v0, v233
	v_cmp_ge_f32_e32 vcc, 0x43800000, v238
	s_cmp_eq_u64 vcc, exec
	s_cbranch_scc0 .Lat_redo_a
	v_add_f32_e32 v232, v232, v0
	v_cvt_pk_bf16_f32 v130, v130, v131
	v_cvt_pk_bf16_f32 v131, v132, v133
	v_cvt_pk_bf16_f32 v132, v134, v135
	v_cvt_pk_bf16_f32 v133, v136, v137
	v_cvt_pk_bf16_f32 v134, v138, v139
	v_cvt_pk_bf16_f32 v135, v140, v141
	v_cvt_pk_bf16_f32 v136, v142, v143
	v_cvt_pk_bf16_f32 v137, v144, v145
	v_add_f32_e32 v244, v244, v233
	v_cvt_pk_bf16_f32 v146, v146, v147
	v_cvt_pk_bf16_f32 v147, v148, v149
	v_cvt_pk_bf16_f32 v148, v150, v151
	v_cvt_pk_bf16_f32 v149, v152, v153
	v_cvt_pk_bf16_f32 v150, v154, v155
	v_cvt_pk_bf16_f32 v151, v156, v157
	v_cvt_pk_bf16_f32 v152, v158, v159
	v_cvt_pk_bf16_f32 v153, v160, v161
	s_waitcnt lgkmcnt(4)
	v_mfma_f32_16x16x32_bf16 v[114:117], v[162:165], v[130:133], v[114:117]
	v_mfma_f32_16x16x32_bf16 v[122:125], v[162:165], v[146:149], v[122:125]
	ds_read_b64_tr_b16 v[162:163], v242 offset:512
	ds_read_b64_tr_b16 v[164:165], v242 offset:8704
	v_mfma_f32_16x16x32_bf16 v[114:117], v[166:169], v[134:137], v[114:117]
	v_mfma_f32_16x16x32_bf16 v[122:125], v[166:169], v[150:153], v[122:125]
	ds_read_b64_tr_b16 v[166:167], v242 offset:16896
	ds_read_b64_tr_b16 v[168:169], v242 offset:25088
	s_waitcnt lgkmcnt(4)
	v_mfma_f32_16x16x32_bf16 v[118:121], v[170:173], v[130:133], v[118:121]
	v_mfma_f32_16x16x32_bf16 v[126:129], v[170:173], v[146:149], v[126:129]
	ds_read_b64_tr_b16 v[170:171], v242 offset:768
	ds_read_b64_tr_b16 v[172:173], v242 offset:8960
	v_mfma_f32_16x16x32_bf16 v[118:121], v[174:177], v[134:137], v[118:121]
	v_mfma_f32_16x16x32_bf16 v[126:129], v[174:177], v[150:153], v[126:129]
	ds_read_b64_tr_b16 v[174:175], v242 offset:17152
	ds_read_b64_tr_b16 v[176:177], v242 offset:25344
	s_waitcnt lgkmcnt(4)
	v_mfma_f32_16x16x32_bf16 v[98:101], v[162:165], v[130:133], v[98:101]
	v_mfma_f32_16x16x32_bf16 v[106:109], v[162:165], v[146:149], v[106:109]
	ds_read_b64_tr_b16 v[162:163], v242 offset:1024
	ds_read_b64_tr_b16 v[164:165], v242 offset:9216
	v_mfma_f32_16x16x32_bf16 v[98:101], v[166:169], v[134:137], v[98:101]
	v_mfma_f32_16x16x32_bf16 v[106:109], v[166:169], v[150:153], v[106:109]
	ds_read_b64_tr_b16 v[166:167], v242 offset:17408
	ds_read_b64_tr_b16 v[168:169], v242 offset:25600
	s_waitcnt lgkmcnt(4)
	v_mfma_f32_16x16x32_bf16 v[102:105], v[170:173], v[130:133], v[102:105]
	v_mfma_f32_16x16x32_bf16 v[110:113], v[170:173], v[146:149], v[110:113]
	ds_read_b64_tr_b16 v[170:171], v242 offset:1280
	ds_read_b64_tr_b16 v[172:173], v242 offset:9472
	v_mfma_f32_16x16x32_bf16 v[102:105], v[174:177], v[134:137], v[102:105]
	v_mfma_f32_16x16x32_bf16 v[110:113], v[174:177], v[150:153], v[110:113]
	ds_read_b64_tr_b16 v[174:175], v242 offset:17664
	ds_read_b64_tr_b16 v[176:177], v242 offset:25856
	s_waitcnt lgkmcnt(4)
	v_mfma_f32_16x16x32_bf16 v[82:85], v[162:165], v[130:133], v[82:85]
	v_mfma_f32_16x16x32_bf16 v[90:93], v[162:165], v[146:149], v[90:93]
	ds_read_b64_tr_b16 v[162:163], v242 offset:1536
	ds_read_b64_tr_b16 v[164:165], v242 offset:9728
	v_mfma_f32_16x16x32_bf16 v[82:85], v[166:169], v[134:137], v[82:85]
	v_mfma_f32_16x16x32_bf16 v[90:93], v[166:169], v[150:153], v[90:93]
	ds_read_b64_tr_b16 v[166:167], v242 offset:17920
	ds_read_b64_tr_b16 v[168:169], v242 offset:26112
	s_waitcnt lgkmcnt(4)
	v_mfma_f32_16x16x32_bf16 v[86:89], v[170:173], v[130:133], v[86:89]
	v_mfma_f32_16x16x32_bf16 v[94:97], v[170:173], v[146:149], v[94:97]
	ds_read_b64_tr_b16 v[170:171], v242 offset:1792
	ds_read_b64_tr_b16 v[172:173], v242 offset:9984
	v_mfma_f32_16x16x32_bf16 v[86:89], v[174:177], v[134:137], v[86:89]
	v_mfma_f32_16x16x32_bf16 v[94:97], v[174:177], v[150:153], v[94:97]
	ds_read_b64_tr_b16 v[174:175], v242 offset:18176
	ds_read_b64_tr_b16 v[176:177], v242 offset:26368
	s_waitcnt lgkmcnt(4)
	v_mfma_f32_16x16x32_bf16 v[66:69], v[162:165], v[130:133], v[66:69]
	v_mfma_f32_16x16x32_bf16 v[74:77], v[162:165], v[146:149], v[74:77]
	ds_read_b64_tr_b16 v[162:163], v242 offset:2048
	ds_read_b64_tr_b16 v[164:165], v242 offset:10240
	v_mfma_f32_16x16x32_bf16 v[66:69], v[166:169], v[134:137], v[66:69]
	v_mfma_f32_16x16x32_bf16 v[74:77], v[166:169], v[150:153], v[74:77]
	ds_read_b64_tr_b16 v[166:167], v242 offset:18432
	ds_read_b64_tr_b16 v[168:169], v242 offset:26624
	s_waitcnt lgkmcnt(4)
	v_mfma_f32_16x16x32_bf16 v[70:73], v[170:173], v[130:133], v[70:73]
	v_mfma_f32_16x16x32_bf16 v[78:81], v[170:173], v[146:149], v[78:81]
	ds_read_b64_tr_b16 v[170:171], v242 offset:2304
	ds_read_b64_tr_b16 v[172:173], v242 offset:10496
	v_mfma_f32_16x16x32_bf16 v[70:73], v[174:177], v[134:137], v[70:73]
	v_mfma_f32_16x16x32_bf16 v[78:81], v[174:177], v[150:153], v[78:81]
	ds_read_b64_tr_b16 v[174:175], v242 offset:18688
	ds_read_b64_tr_b16 v[176:177], v242 offset:26880
	s_waitcnt lgkmcnt(4)
	v_mfma_f32_16x16x32_bf16 v[50:53], v[162:165], v[130:133], v[50:53]
	v_mfma_f32_16x16x32_bf16 v[58:61], v[162:165], v[146:149], v[58:61]
	ds_read_b64_tr_b16 v[162:163], v242 offset:2560
	ds_read_b64_tr_b16 v[164:165], v242 offset:10752
	v_mfma_f32_16x16x32_bf16 v[50:53], v[166:169], v[134:137], v[50:53]
	v_mfma_f32_16x16x32_bf16 v[58:61], v[166:169], v[150:153], v[58:61]
	ds_read_b64_tr_b16 v[166:167], v242 offset:18944
	ds_read_b64_tr_b16 v[168:169], v242 offset:27136
	s_waitcnt lgkmcnt(4)
	v_mfma_f32_16x16x32_bf16 v[54:57], v[170:173], v[130:133], v[54:57]
	v_mfma_f32_16x16x32_bf16 v[62:65], v[170:173], v[146:149], v[62:65]
	ds_read_b64_tr_b16 v[170:171], v242 offset:2816
	ds_read_b64_tr_b16 v[172:173], v242 offset:11008
	v_mfma_f32_16x16x32_bf16 v[54:57], v[174:177], v[134:137], v[54:57]
	v_mfma_f32_16x16x32_bf16 v[62:65], v[174:177], v[150:153], v[62:65]
	ds_read_b64_tr_b16 v[174:175], v242 offset:19200
	ds_read_b64_tr_b16 v[176:177], v242 offset:27392
	s_waitcnt lgkmcnt(4)
	v_mfma_f32_16x16x32_bf16 v[34:37], v[162:165], v[130:133], v[34:37]
	v_mfma_f32_16x16x32_bf16 v[42:45], v[162:165], v[146:149], v[42:45]
	ds_read_b64_tr_b16 v[162:163], v242 offset:3072
	ds_read_b64_tr_b16 v[164:165], v242 offset:11264
	v_mfma_f32_16x16x32_bf16 v[34:37], v[166:169], v[134:137], v[34:37]
	v_mfma_f32_16x16x32_bf16 v[42:45], v[166:169], v[150:153], v[42:45]
	ds_read_b64_tr_b16 v[166:167], v242 offset:19456
	ds_read_b64_tr_b16 v[168:169], v242 offset:27648
	s_waitcnt lgkmcnt(4)
	v_mfma_f32_16x16x32_bf16 v[38:41], v[170:173], v[130:133], v[38:41]
	v_mfma_f32_16x16x32_bf16 v[46:49], v[170:173], v[146:149], v[46:49]
	ds_read_b64_tr_b16 v[170:171], v242 offset:3328
	ds_read_b64_tr_b16 v[172:173], v242 offset:11520
	v_mfma_f32_16x16x32_bf16 v[38:41], v[174:177], v[134:137], v[38:41]
	v_mfma_f32_16x16x32_bf16 v[46:49], v[174:177], v[150:153], v[46:49]
	ds_read_b64_tr_b16 v[174:175], v242 offset:19712
	ds_read_b64_tr_b16 v[176:177], v242 offset:27904
	s_waitcnt lgkmcnt(4)
	v_mfma_f32_16x16x32_bf16 v[18:21], v[162:165], v[130:133], v[18:21]
	v_mfma_f32_16x16x32_bf16 v[26:29], v[162:165], v[146:149], v[26:29]
	ds_read_b64_tr_b16 v[162:163], v242 offset:3584
	ds_read_b64_tr_b16 v[164:165], v242 offset:11776
	v_mfma_f32_16x16x32_bf16 v[18:21], v[166:169], v[134:137], v[18:21]
	v_mfma_f32_16x16x32_bf16 v[26:29], v[166:169], v[150:153], v[26:29]
	ds_read_b64_tr_b16 v[166:167], v242 offset:19968
	ds_read_b64_tr_b16 v[168:169], v242 offset:28160
	s_waitcnt lgkmcnt(4)
	v_mfma_f32_16x16x32_bf16 v[22:25], v[170:173], v[130:133], v[22:25]
	v_mfma_f32_16x16x32_bf16 v[30:33], v[170:173], v[146:149], v[30:33]
	ds_read_b64_tr_b16 v[170:171], v242 offset:3840
	ds_read_b64_tr_b16 v[172:173], v242 offset:12032
	v_mfma_f32_16x16x32_bf16 v[22:25], v[174:177], v[134:137], v[22:25]
	v_mfma_f32_16x16x32_bf16 v[30:33], v[174:177], v[150:153], v[30:33]
	ds_read_b64_tr_b16 v[174:175], v242 offset:20224
	ds_read_b64_tr_b16 v[176:177], v242 offset:28416
	s_waitcnt lgkmcnt(4)
	v_mfma_f32_16x16x32_bf16 v[2:5], v[162:165], v[130:133], v[2:5]
	v_mfma_f32_16x16x32_bf16 v[10:13], v[162:165], v[146:149], v[10:13]
	v_mfma_f32_16x16x32_bf16 v[2:5], v[166:169], v[134:137], v[2:5]
	v_mfma_f32_16x16x32_bf16 v[10:13], v[166:169], v[150:153], v[10:13]
	s_waitcnt lgkmcnt(0)
	v_mfma_f32_16x16x32_bf16 v[6:9], v[170:173], v[130:133], v[6:9]
	v_mfma_f32_16x16x32_bf16 v[14:17], v[170:173], v[146:149], v[14:17]
	v_mfma_f32_16x16x32_bf16 v[6:9], v[174:177], v[134:137], v[6:9]
	v_mfma_f32_16x16x32_bf16 v[14:17], v[174:177], v[150:153], v[14:17]
	s_branch .Lat_end_a
.Lat_redo_a:
	s_mov_b32 s84, 1
	s_waitcnt lgkmcnt(0)
	v_mov_b32_e32 v234, v221
	v_xor_b32_e32 v235, 64, v234
	v_xor_b32_e32 v236, 0x80, v234
	v_xor_b32_e32 v237, 0xc0, v234
	ds_read_b128 v[162:165], v234
	s_waitcnt lgkmcnt(0)
	v_mfma_f32_16x16x32_bf16 v[130:133], v[162:165], v[178:181], v[246:249]
	v_mfma_f32_16x16x32_bf16 v[146:149], v[162:165], v[194:197], v[250:253]
	ds_read_b128 v[162:165], v235
	s_waitcnt lgkmcnt(0)
	v_mfma_f32_16x16x32_bf16 v[130:133], v[162:165], v[182:185], v[130:133]
	v_mfma_f32_16x16x32_bf16 v[146:149], v[162:165], v[198:201], v[146:149]
	ds_read_b128 v[162:165], v236
	s_waitcnt lgkmcnt(0)
	v_mfma_f32_16x16x32_bf16 v[130:133], v[162:165], v[186:189], v[130:133]
	v_mfma_f32_16x16x32_bf16 v[146:149], v[162:165], v[202:205], v[146:149]
	ds_read_b128 v[162:165], v237
	s_waitcnt lgkmcnt(0)
	v_mfma_f32_16x16x32_bf16 v[130:133], v[162:165], v[190:193], v[130:133]
	v_mfma_f32_16x16x32_bf16 v[146:149], v[162:165], v[206:209], v[146:149]
	ds_read_b128 v[162:165], v234 offset:4096
	s_waitcnt lgkmcnt(0)
	v_mfma_f32_16x16x32_bf16 v[134:137], v[162:165], v[178:181], v[246:249]
	v_mfma_f32_16x16x32_bf16 v[150:153], v[162:165], v[194:197], v[250:253]
	ds_read_b128 v[162:165], v235 offset:4096
	s_waitcnt lgkmcnt(0)
	v_mfma_f32_16x16x32_bf16 v[134:137], v[162:165], v[182:185], v[134:137]
	v_mfma_f32_16x16x32_bf16 v[150:153], v[162:165], v[198:201], v[150:153]
	ds_read_b128 v[162:165], v236 offset:4096
	s_waitcnt lgkmcnt(0)
	v_mfma_f32_16x16x32_bf16 v[134:137], v[162:165], v[186:189], v[134:137]
	v_mfma_f32_16x16x32_bf16 v[150:153], v[162:165], v[202:205], v[150:153]
	ds_read_b128 v[162:165], v237 offset:4096
	s_waitcnt lgkmcnt(0)
	v_mfma_f32_16x16x32_bf16 v[134:137], v[162:165], v[190:193], v[134:137]
	v_mfma_f32_16x16x32_bf16 v[150:153], v[162:165], v[206:209], v[150:153]
	ds_read_b128 v[162:165], v234 offset:8192
	s_waitcnt lgkmcnt(0)
	v_mfma_f32_16x16x32_bf16 v[138:141], v[162:165], v[178:181], v[246:249]
	v_mfma_f32_16x16x32_bf16 v[154:157], v[162:165], v[194:197], v[250:253]
	ds_read_b128 v[162:165], v235 offset:8192
	s_waitcnt lgkmcnt(0)
	v_mfma_f32_16x16x32_bf16 v[138:141], v[162:165], v[182:185], v[138:141]
	v_mfma_f32_16x16x32_bf16 v[154:157], v[162:165], v[198:201], v[154:157]
	ds_read_b128 v[162:165], v236 offset:8192
	s_waitcnt lgkmcnt(0)
	v_mfma_f32_16x16x32_bf16 v[138:141], v[162:165], v[186:189], v[138:141]
	v_mfma_f32_16x16x32_bf16 v[154:157], v[162:165], v[202:205], v[154:157]
	ds_read_b128 v[162:165], v237 offset:8192
	s_waitcnt lgkmcnt(0)
	v_mfma_f32_16x16x32_bf16 v[138:141], v[162:165], v[190:193], v[138:141]
	v_mfma_f32_16x16x32_bf16 v[154:157], v[162:165], v[206:209], v[154:157]
	ds_read_b128 v[162:165], v234 offset:12288
	s_waitcnt lgkmcnt(0)
	v_mfma_f32_16x16x32_bf16 v[142:145], v[162:165], v[178:181], v[246:249]
	v_mfma_f32_16x16x32_bf16 v[158:161], v[162:165], v[194:197], v[250:253]
	ds_read_b128 v[162:165], v235 offset:12288
	s_waitcnt lgkmcnt(0)
	v_mfma_f32_16x16x32_bf16 v[142:145], v[162:165], v[182:185], v[142:145]
	v_mfma_f32_16x16x32_bf16 v[158:161], v[162:165], v[198:201], v[158:161]
	ds_read_b128 v[162:165], v236 offset:12288
	s_waitcnt lgkmcnt(0)
	v_mfma_f32_16x16x32_bf16 v[142:145], v[162:165], v[186:189], v[142:145]
	v_mfma_f32_16x16x32_bf16 v[158:161], v[162:165], v[202:205], v[158:161]
	ds_read_b128 v[162:165], v237 offset:12288
	s_waitcnt lgkmcnt(0)
	v_mfma_f32_16x16x32_bf16 v[142:145], v[162:165], v[190:193], v[142:145]
	v_mfma_f32_16x16x32_bf16 v[158:161], v[162:165], v[206:209], v[158:161]
	ds_read_b64_tr_b16 v[162:163], v242 offset:0
	ds_read_b64_tr_b16 v[164:165], v242 offset:8192
	ds_read_b64_tr_b16 v[166:167], v242 offset:16384
	ds_read_b64_tr_b16 v[168:169], v242 offset:24576
	ds_read_b64_tr_b16 v[170:171], v242 offset:256
	ds_read_b64_tr_b16 v[172:173], v242 offset:8448
	ds_read_b64_tr_b16 v[174:175], v242 offset:16640
	ds_read_b64_tr_b16 v[176:177], v242 offset:24832
	s_nop 7
	s_branch .Lat_dt_a

.Lat_diag_a:
	s_nop 7
	v_subrev_u32_e32 v234, 0, v223
	v_cmp_gt_i32_e64 s[4:5], 0, v234
	v_med3_i32 v234, v234, 0, s81
	v_lshl_add_u32 v234, v234, 2, s80
	ds_read_b32 v238, v234
	v_subrev_u32_e32 v235, 1, v223
	v_cmp_gt_i32_e64 s[6:7], 0, v235
	v_med3_i32 v235, v235, 0, s81
	v_lshl_add_u32 v235, v235, 2, s80
	ds_read_b32 v239, v235
	v_subrev_u32_e32 v236, 2, v223
	v_cmp_gt_i32_e64 s[8:9], 0, v236
	v_med3_i32 v236, v236, 0, s81
	v_lshl_add_u32 v236, v236, 2, s80
	ds_read_b32 v240, v236
	v_subrev_u32_e32 v237, 3, v223
	v_cmp_gt_i32_e64 s[10:11], 0, v237
	v_med3_i32 v237, v237, 0, s81
	v_lshl_add_u32 v237, v237, 2, s80
	ds_read_b32 v241, v237
	s_waitcnt lgkmcnt(0)
	v_add_f32_e32 v130, v130, v238
	v_cndmask_b32_e64 v130, v130, v216, s[4:5]
	v_add_f32_e32 v131, v131, v239
	v_cndmask_b32_e64 v131, v131, v216, s[6:7]
	v_add_f32_e32 v132, v132, v240
	v_cndmask_b32_e64 v132, v132, v216, s[8:9]
	v_add_f32_e32 v133, v133, v241
	v_cndmask_b32_e64 v133, v133, v216, s[10:11]
	v_subrev_u32_e32 v234, 16, v223
	v_cmp_gt_i32_e64 s[4:5], 0, v234
	v_med3_i32 v234, v234, 0, s81
	v_lshl_add_u32 v234, v234, 2, s80
	ds_read_b32 v238, v234
	v_subrev_u32_e32 v235, 17, v223
	v_cmp_gt_i32_e64 s[6:7], 0, v235
	v_med3_i32 v235, v235, 0, s81
	v_lshl_add_u32 v235, v235, 2, s80
	ds_read_b32 v239, v235
	v_subrev_u32_e32 v236, 18, v223
	v_cmp_gt_i32_e64 s[8:9], 0, v236
	v_med3_i32 v236, v236, 0, s81
	v_lshl_add_u32 v236, v236, 2, s80
	ds_read_b32 v240, v236
	v_subrev_u32_e32 v237, 19, v223
	v_cmp_gt_i32_e64 s[10:11], 0, v237
	v_med3_i32 v237, v237, 0, s81
	v_lshl_add_u32 v237, v237, 2, s80
	ds_read_b32 v241, v237
	s_waitcnt lgkmcnt(0)
	v_add_f32_e32 v134, v134, v238
	v_cndmask_b32_e64 v134, v134, v216, s[4:5]
	v_add_f32_e32 v135, v135, v239
	v_cndmask_b32_e64 v135, v135, v216, s[6:7]
	v_add_f32_e32 v136, v136, v240
	v_cndmask_b32_e64 v136, v136, v216, s[8:9]
	v_add_f32_e32 v137, v137, v241
	v_cndmask_b32_e64 v137, v137, v216, s[10:11]
	v_subrev_u32_e32 v234, 32, v223
	v_cmp_gt_i32_e64 s[4:5], 0, v234
	v_med3_i32 v234, v234, 0, s81
	v_lshl_add_u32 v234, v234, 2, s80
	ds_read_b32 v238, v234
	v_subrev_u32_e32 v235, 33, v223
	v_cmp_gt_i32_e64 s[6:7], 0, v235
	v_med3_i32 v235, v235, 0, s81
	v_lshl_add_u32 v235, v235, 2, s80
	ds_read_b32 v239, v235
	v_subrev_u32_e32 v236, 34, v223
	v_cmp_gt_i32_e64 s[8:9], 0, v236
	v_med3_i32 v236, v236, 0, s81
	v_lshl_add_u32 v236, v236, 2, s80
	ds_read_b32 v240, v236
	v_subrev_u32_e32 v237, 35, v223
	v_cmp_gt_i32_e64 s[10:11], 0, v237
	v_med3_i32 v237, v237, 0, s81
	v_lshl_add_u32 v237, v237, 2, s80
	ds_read_b32 v241, v237
	s_waitcnt lgkmcnt(0)
	v_add_f32_e32 v138, v138, v238
	v_cndmask_b32_e64 v138, v138, v216, s[4:5]
	v_add_f32_e32 v139, v139, v239
	v_cndmask_b32_e64 v139, v139, v216, s[6:7]
	v_add_f32_e32 v140, v140, v240
	v_cndmask_b32_e64 v140, v140, v216, s[8:9]
	v_add_f32_e32 v141, v141, v241
	v_cndmask_b32_e64 v141, v141, v216, s[10:11]
	v_subrev_u32_e32 v234, 48, v223
	v_cmp_gt_i32_e64 s[4:5], 0, v234
	v_med3_i32 v234, v234, 0, s81
	v_lshl_add_u32 v234, v234, 2, s80
	ds_read_b32 v238, v234
	v_subrev_u32_e32 v235, 49, v223
	v_cmp_gt_i32_e64 s[6:7], 0, v235
	v_med3_i32 v235, v235, 0, s81
	v_lshl_add_u32 v235, v235, 2, s80
	ds_read_b32 v239, v235
	v_subrev_u32_e32 v236, 50, v223
	v_cmp_gt_i32_e64 s[8:9], 0, v236
	v_med3_i32 v236, v236, 0, s81
	v_lshl_add_u32 v236, v236, 2, s80
	ds_read_b32 v240, v236
	v_subrev_u32_e32 v237, 51, v223
	v_cmp_gt_i32_e64 s[10:11], 0, v237
	v_med3_i32 v237, v237, 0, s81
	v_lshl_add_u32 v237, v237, 2, s80
	ds_read_b32 v241, v237
	s_waitcnt lgkmcnt(0)
	v_add_f32_e32 v142, v142, v238
	v_cndmask_b32_e64 v142, v142, v216, s[4:5]
	v_add_f32_e32 v143, v143, v239
	v_cndmask_b32_e64 v143, v143, v216, s[6:7]
	v_add_f32_e32 v144, v144, v240
	v_cndmask_b32_e64 v144, v144, v216, s[8:9]
	v_add_f32_e32 v145, v145, v241
	v_cndmask_b32_e64 v145, v145, v216, s[10:11]
	v_subrev_u32_e32 v234, -16, v223
	v_cmp_gt_i32_e64 s[4:5], 0, v234
	v_med3_i32 v234, v234, 0, s81
	v_lshl_add_u32 v234, v234, 2, s80
	ds_read_b32 v238, v234
	v_subrev_u32_e32 v235, -15, v223
	v_cmp_gt_i32_e64 s[6:7], 0, v235
	v_med3_i32 v235, v235, 0, s81
	v_lshl_add_u32 v235, v235, 2, s80
	ds_read_b32 v239, v235
	v_subrev_u32_e32 v236, -14, v223
	v_cmp_gt_i32_e64 s[8:9], 0, v236
	v_med3_i32 v236, v236, 0, s81
	v_lshl_add_u32 v236, v236, 2, s80
	ds_read_b32 v240, v236
	v_subrev_u32_e32 v237, -13, v223
	v_cmp_gt_i32_e64 s[10:11], 0, v237
	v_med3_i32 v237, v237, 0, s81
	v_lshl_add_u32 v237, v237, 2, s80
	ds_read_b32 v241, v237
	s_waitcnt lgkmcnt(0)
	v_add_f32_e32 v146, v146, v238
	v_cndmask_b32_e64 v146, v146, v216, s[4:5]
	v_add_f32_e32 v147, v147, v239
	v_cndmask_b32_e64 v147, v147, v216, s[6:7]
	v_add_f32_e32 v148, v148, v240
	v_cndmask_b32_e64 v148, v148, v216, s[8:9]
	v_add_f32_e32 v149, v149, v241
	v_cndmask_b32_e64 v149, v149, v216, s[10:11]
	v_subrev_u32_e32 v234, 0, v223
	v_cmp_gt_i32_e64 s[4:5], 0, v234
	v_med3_i32 v234, v234, 0, s81
	v_lshl_add_u32 v234, v234, 2, s80
	ds_read_b32 v238, v234
	v_subrev_u32_e32 v235, 1, v223
	v_cmp_gt_i32_e64 s[6:7], 0, v235
	v_med3_i32 v235, v235, 0, s81
	v_lshl_add_u32 v235, v235, 2, s80
	ds_read_b32 v239, v235
	v_subrev_u32_e32 v236, 2, v223
	v_cmp_gt_i32_e64 s[8:9], 0, v236
	v_med3_i32 v236, v236, 0, s81
	v_lshl_add_u32 v236, v236, 2, s80
	ds_read_b32 v240, v236
	v_subrev_u32_e32 v237, 3, v223
	v_cmp_gt_i32_e64 s[10:11], 0, v237
	v_med3_i32 v237, v237, 0, s81
	v_lshl_add_u32 v237, v237, 2, s80
	ds_read_b32 v241, v237
	s_waitcnt lgkmcnt(0)
	v_add_f32_e32 v150, v150, v238
	v_cndmask_b32_e64 v150, v150, v216, s[4:5]
	v_add_f32_e32 v151, v151, v239
	v_cndmask_b32_e64 v151, v151, v216, s[6:7]
	v_add_f32_e32 v152, v152, v240
	v_cndmask_b32_e64 v152, v152, v216, s[8:9]
	v_add_f32_e32 v153, v153, v241
	v_cndmask_b32_e64 v153, v153, v216, s[10:11]
	v_subrev_u32_e32 v234, 16, v223
	v_cmp_gt_i32_e64 s[4:5], 0, v234
	v_med3_i32 v234, v234, 0, s81
	v_lshl_add_u32 v234, v234, 2, s80
	ds_read_b32 v238, v234
	v_subrev_u32_e32 v235, 17, v223
	v_cmp_gt_i32_e64 s[6:7], 0, v235
	v_med3_i32 v235, v235, 0, s81
	v_lshl_add_u32 v235, v235, 2, s80
	ds_read_b32 v239, v235
	v_subrev_u32_e32 v236, 18, v223
	v_cmp_gt_i32_e64 s[8:9], 0, v236
	v_med3_i32 v236, v236, 0, s81
	v_lshl_add_u32 v236, v236, 2, s80
	ds_read_b32 v240, v236
	v_subrev_u32_e32 v237, 19, v223
	v_cmp_gt_i32_e64 s[10:11], 0, v237
	v_med3_i32 v237, v237, 0, s81
	v_lshl_add_u32 v237, v237, 2, s80
	ds_read_b32 v241, v237
	s_waitcnt lgkmcnt(0)
	v_add_f32_e32 v154, v154, v238
	v_cndmask_b32_e64 v154, v154, v216, s[4:5]
	v_add_f32_e32 v155, v155, v239
	v_cndmask_b32_e64 v155, v155, v216, s[6:7]
	v_add_f32_e32 v156, v156, v240
	v_cndmask_b32_e64 v156, v156, v216, s[8:9]
	v_add_f32_e32 v157, v157, v241
	v_cndmask_b32_e64 v157, v157, v216, s[10:11]
	v_subrev_u32_e32 v234, 32, v223
	v_cmp_gt_i32_e64 s[4:5], 0, v234
	v_med3_i32 v234, v234, 0, s81
	v_lshl_add_u32 v234, v234, 2, s80
	ds_read_b32 v238, v234
	v_subrev_u32_e32 v235, 33, v223
	v_cmp_gt_i32_e64 s[6:7], 0, v235
	v_med3_i32 v235, v235, 0, s81
	v_lshl_add_u32 v235, v235, 2, s80
	ds_read_b32 v239, v235
	v_subrev_u32_e32 v236, 34, v223
	v_cmp_gt_i32_e64 s[8:9], 0, v236
	v_med3_i32 v236, v236, 0, s81
	v_lshl_add_u32 v236, v236, 2, s80
	ds_read_b32 v240, v236
	v_subrev_u32_e32 v237, 35, v223
	v_cmp_gt_i32_e64 s[10:11], 0, v237
	v_med3_i32 v237, v237, 0, s81
	v_lshl_add_u32 v237, v237, 2, s80
	ds_read_b32 v241, v237
	s_waitcnt lgkmcnt(0)
	v_add_f32_e32 v158, v158, v238
	v_cndmask_b32_e64 v158, v158, v216, s[4:5]
	v_add_f32_e32 v159, v159, v239
	v_cndmask_b32_e64 v159, v159, v216, s[6:7]
	v_add_f32_e32 v160, v160, v240
	v_cndmask_b32_e64 v160, v160, v216, s[8:9]
	v_add_f32_e32 v161, v161, v241
	v_cndmask_b32_e64 v161, v161, v216, s[10:11]
	v_mov_b32_e32 v234, v221
	v_xor_b32_e32 v235, 64, v234
	v_xor_b32_e32 v236, 0x80, v234
	v_xor_b32_e32 v237, 0xc0, v234
	s_branch .Lat_sm_a
.Lat_end_a:
.Lat_next0:
	s_add_i32 s58, s58, 1
	v_add_u32_e32 v223, 0xffffffc0, v223
	s_addk_i32 s91, 0x40
	s_add_u32 s50, s50, 0x80000
	s_addc_u32 s51, s51, 0
	s_mov_b32 s94, 0
	s_cmp_gt_u32 s58, s88
	s_cbranch_scc1 .Lat_final
	s_waitcnt vmcnt(0) lgkmcnt(0)
	s_barrier
	s_cmp_gt_u32 s58, s89
	s_cbranch_scc1 .Lat_inactive1
	ds_read_b128 v[162:165], v234 offset:32768
	ds_read_b128 v[166:169], v235 offset:32768
	ds_read_b128 v[170:173], v236 offset:32768
	ds_read_b128 v[174:177], v237 offset:32768
	s_add_i32 m0, s97, 0x0
	s_nop 0
	global_load_lds_dwordx4 v231, s[50:51]
	s_add_i32 m0, s97, 0x400
	s_nop 0
	global_load_lds_dwordx4 v229, s[50:51]
	s_waitcnt lgkmcnt(2)
	v_mfma_f32_16x16x32_bf16 v[130:133], v[162:165], v[178:181], v[246:249]
	v_mfma_f32_16x16x32_bf16 v[146:149], v[162:165], v[194:197], v[250:253]
	ds_read_b128 v[162:165], v234 offset:36864
	v_mfma_f32_16x16x32_bf16 v[130:133], v[166:169], v[182:185], v[130:133]
	s_add_i32 m0, s97, 0x800
	v_mfma_f32_16x16x32_bf16 v[146:149], v[166:169], v[198:201], v[146:149]
	ds_read_b128 v[166:169], v235 offset:36864
	global_load_lds_dwordx4 v227, s[50:51]
	s_waitcnt lgkmcnt(2)
	v_mfma_f32_16x16x32_bf16 v[130:133], v[170:173], v[186:189], v[130:133]
	v_mfma_f32_16x16x32_bf16 v[146:149], v[170:173], v[202:205], v[146:149]
	ds_read_b128 v[170:173], v236 offset:36864
	v_mfma_f32_16x16x32_bf16 v[130:133], v[174:177], v[190:193], v[130:133]
	s_add_i32 m0, s97, 0xc00
	v_mfma_f32_16x16x32_bf16 v[146:149], v[174:177], v[206:209], v[146:149]
	ds_read_b128 v[174:177], v237 offset:36864
	global_load_lds_dwordx4 v225, s[50:51]
	s_waitcnt lgkmcnt(2)
	v_mfma_f32_16x16x32_bf16 v[134:137], v[162:165], v[178:181], v[246:249]
	v_mfma_f32_16x16x32_bf16 v[150:153], v[162:165], v[194:197], v[250:253]
	ds_read_b128 v[162:165], v234 offset:40960
	v_mfma_f32_16x16x32_bf16 v[134:137], v[166:169], v[182:185], v[134:137]
	s_add_i32 m0, s97, 0x1000
	v_mfma_f32_16x16x32_bf16 v[150:153], v[166:169], v[198:201], v[150:153]
	ds_read_b128 v[166:169], v235 offset:40960
	global_load_lds_dwordx4 v230, s[50:51]
	s_waitcnt lgkmcnt(2)
	v_mfma_f32_16x16x32_bf16 v[134:137], v[170:173], v[186:189], v[134:137]
	v_mfma_f32_16x16x32_bf16 v[150:153], v[170:173], v[202:205], v[150:153]
	ds_read_b128 v[170:173], v236 offset:40960
	v_mfma_f32_16x16x32_bf16 v[134:137], v[174:177], v[190:193], v[134:137]
	s_add_i32 m0, s97, 0x1400
	v_mfma_f32_16x16x32_bf16 v[150:153], v[174:177], v[206:209], v[150:153]
	ds_read_b128 v[174:177], v237 offset:40960
	global_load_lds_dwordx4 v228, s[50:51]
	s_waitcnt lgkmcnt(2)
	v_mfma_f32_16x16x32_bf16 v[138:141], v[162:165], v[178:181], v[246:249]
	v_mfma_f32_16x16x32_bf16 v[154:157], v[162:165], v[194:197], v[250:253]
	ds_read_b128 v[162:165], v234 offset:45056
	v_mfma_f32_16x16x32_bf16 v[138:141], v[166:169], v[182:185], v[138:141]
	s_add_i32 m0, s97, 0x1800
	v_mfma_f32_16x16x32_bf16 v[154:157], v[166:169], v[198:201], v[154:157]
	ds_read_b128 v[166:169], v235 offset:45056
	global_load_lds_dwordx4 v226, s[50:51]
	s_waitcnt lgkmcnt(2)
	v_mfma_f32_16x16x32_bf16 v[138:141], v[170:173], v[186:189], v[138:141]
	v_mfma_f32_16x16x32_bf16 v[154:157], v[170:173], v[202:205], v[154:157]
	ds_read_b128 v[170:173], v236 offset:45056
	v_mfma_f32_16x16x32_bf16 v[138:141], v[174:177], v[190:193], v[138:141]
	s_add_i32 m0, s97, 0x1c00
	v_mfma_f32_16x16x32_bf16 v[154:157], v[174:177], v[206:209], v[154:157]
	ds_read_b128 v[174:177], v237 offset:45056
	global_load_lds_dwordx4 v224, s[50:51]
	s_waitcnt lgkmcnt(2)
	v_mfma_f32_16x16x32_bf16 v[142:145], v[162:165], v[178:181], v[246:249]
	v_mfma_f32_16x16x32_bf16 v[158:161], v[162:165], v[194:197], v[250:253]
	ds_read_b64_tr_b16 v[162:163], v242 offset:32768
	ds_read_b64_tr_b16 v[164:165], v242 offset:40960
	v_mfma_f32_16x16x32_bf16 v[142:145], v[166:169], v[182:185], v[142:145]
	v_mfma_f32_16x16x32_bf16 v[158:161], v[166:169], v[198:201], v[158:161]
	ds_read_b64_tr_b16 v[166:167], v242 offset:49152
	ds_read_b64_tr_b16 v[168:169], v242 offset:57344
	s_waitcnt lgkmcnt(4)
	v_mfma_f32_16x16x32_bf16 v[142:145], v[170:173], v[186:189], v[142:145]
	v_mfma_f32_16x16x32_bf16 v[158:161], v[170:173], v[202:205], v[158:161]
	ds_read_b64_tr_b16 v[170:171], v242 offset:33024
	ds_read_b64_tr_b16 v[172:173], v242 offset:41216
	v_mfma_f32_16x16x32_bf16 v[142:145], v[174:177], v[190:193], v[142:145]
	v_mfma_f32_16x16x32_bf16 v[158:161], v[174:177], v[206:209], v[158:161]
	ds_read_b64_tr_b16 v[174:175], v242 offset:49408
	ds_read_b64_tr_b16 v[176:177], v242 offset:57600

.Lat_exp_c:
	v_exp_f32_e32 v130, v130
	v_exp_f32_e32 v131, v131
	v_exp_f32_e32 v132, v132
	v_add_f32_e32 v0, v130, v131
	v_exp_f32_e32 v133, v133
	v_add_f32_e32 v0, v0, v132
	v_exp_f32_e32 v134, v134
	v_add_f32_e32 v0, v0, v133
	v_exp_f32_e32 v135, v135
	v_add_f32_e32 v0, v0, v134
	v_exp_f32_e32 v136, v136
	v_add_f32_e32 v0, v0, v135
	v_exp_f32_e32 v137, v137
	v_add_f32_e32 v0, v0, v136
	v_exp_f32_e32 v138, v138
	v_add_f32_e32 v0, v0, v137
	v_exp_f32_e32 v139, v139
	v_add_f32_e32 v0, v0, v138
	v_exp_f32_e32 v140, v140
	v_add_f32_e32 v0, v0, v139
	v_exp_f32_e32 v141, v141
	v_add_f32_e32 v0, v0, v140
	v_exp_f32_e32 v142, v142
	v_add_f32_e32 v0, v0, v141
	v_exp_f32_e32 v143, v143
	v_add_f32_e32 v0, v0, v142
	v_exp_f32_e32 v144, v144
	v_add_f32_e32 v0, v0, v143
	v_exp_f32_e32 v145, v145
	v_add_f32_e32 v0, v0, v144
	v_exp_f32_e32 v146, v146
	v_exp_f32_e32 v147, v147
	v_exp_f32_e32 v148, v148
	v_add_f32_e32 v233, v146, v147
	v_exp_f32_e32 v149, v149
	v_add_f32_e32 v233, v233, v148
	v_exp_f32_e32 v150, v150
	v_add_f32_e32 v233, v233, v149
	v_exp_f32_e32 v151, v151
	v_add_f32_e32 v233, v233, v150
	v_exp_f32_e32 v152, v152
	v_add_f32_e32 v233, v233, v151
	v_exp_f32_e32 v153, v153
	v_add_f32_e32 v233, v233, v152
	v_exp_f32_e32 v154, v154
	v_add_f32_e32 v233, v233, v153
	v_exp_f32_e32 v155, v155
	v_add_f32_e32 v233, v233, v154
	v_exp_f32_e32 v156, v156
	v_add_f32_e32 v233, v233, v155
	v_exp_f32_e32 v157, v157
	v_add_f32_e32 v233, v233, v156
	v_exp_f32_e32 v158, v158
	v_add_f32_e32 v233, v233, v157
	v_exp_f32_e32 v159, v159
	v_add_f32_e32 v233, v233, v158
	v_exp_f32_e32 v160, v160
	v_add_f32_e32 v233, v233, v159
	v_exp_f32_e32 v161, v161
	v_add_f32_e32 v233, v233, v160
	v_add_f32_e32 v0, v0, v145
	v_add_f32_e32 v233, v233, v161
	v_max_f32_e32 v238, v0, v233
	v_cmp_ge_f32_e32 vcc, 0x43800000, v238
	s_cmp_eq_u64 vcc, exec
	s_cbranch_scc0 .Lat_redo_c
	v_add_f32_e32 v232, v232, v0
	v_cvt_pk_bf16_f32 v130, v130, v131
	v_cvt_pk_bf16_f32 v131, v132, v133
	v_cvt_pk_bf16_f32 v132, v134, v135
	v_cvt_pk_bf16_f32 v133, v136, v137
	v_cvt_pk_bf16_f32 v134, v138, v139
	v_cvt_pk_bf16_f32 v135, v140, v141
	v_cvt_pk_bf16_f32 v136, v142, v143
	v_cvt_pk_bf16_f32 v137, v144, v145
	v_add_f32_e32 v244, v244, v233
	v_cvt_pk_bf16_f32 v146, v146, v147
	v_cvt_pk_bf16_f32 v147, v148, v149
	v_cvt_pk_bf16_f32 v148, v150, v151
	v_cvt_pk_bf16_f32 v149, v152, v153
	v_cvt_pk_bf16_f32 v150, v154, v155
	v_cvt_pk_bf16_f32 v151, v156, v157
	v_cvt_pk_bf16_f32 v152, v158, v159
	v_cvt_pk_bf16_f32 v153, v160, v161
	s_waitcnt lgkmcnt(4)
	v_mfma_f32_16x16x32_bf16 v[114:117], v[162:165], v[130:133], v[114:117]
	v_mfma_f32_16x16x32_bf16 v[122:125], v[162:165], v[146:149], v[122:125]
	ds_read_b64_tr_b16 v[162:163], v242 offset:33280
	ds_read_b64_tr_b16 v[164:165], v242 offset:41472
	v_mfma_f32_16x16x32_bf16 v[114:117], v[166:169], v[134:137], v[114:117]
	v_mfma_f32_16x16x32_bf16 v[122:125], v[166:169], v[150:153], v[122:125]
	ds_read_b64_tr_b16 v[166:167], v242 offset:49664
	ds_read_b64_tr_b16 v[168:169], v242 offset:57856
	s_waitcnt lgkmcnt(4)
	v_mfma_f32_16x16x32_bf16 v[118:121], v[170:173], v[130:133], v[118:121]
	v_mfma_f32_16x16x32_bf16 v[126:129], v[170:173], v[146:149], v[126:129]
	ds_read_b64_tr_b16 v[170:171], v242 offset:33536
	ds_read_b64_tr_b16 v[172:173], v242 offset:41728
	v_mfma_f32_16x16x32_bf16 v[118:121], v[174:177], v[134:137], v[118:121]
	v_mfma_f32_16x16x32_bf16 v[126:129], v[174:177], v[150:153], v[126:129]
	ds_read_b64_tr_b16 v[174:175], v242 offset:49920
	ds_read_b64_tr_b16 v[176:177], v242 offset:58112
	s_waitcnt lgkmcnt(4)
	v_mfma_f32_16x16x32_bf16 v[98:101], v[162:165], v[130:133], v[98:101]
	v_mfma_f32_16x16x32_bf16 v[106:109], v[162:165], v[146:149], v[106:109]
	ds_read_b64_tr_b16 v[162:163], v242 offset:33792
	ds_read_b64_tr_b16 v[164:165], v242 offset:41984
	v_mfma_f32_16x16x32_bf16 v[98:101], v[166:169], v[134:137], v[98:101]
	v_mfma_f32_16x16x32_bf16 v[106:109], v[166:169], v[150:153], v[106:109]
	ds_read_b64_tr_b16 v[166:167], v242 offset:50176
	ds_read_b64_tr_b16 v[168:169], v242 offset:58368
	s_waitcnt lgkmcnt(4)
	v_mfma_f32_16x16x32_bf16 v[102:105], v[170:173], v[130:133], v[102:105]
	v_mfma_f32_16x16x32_bf16 v[110:113], v[170:173], v[146:149], v[110:113]
	ds_read_b64_tr_b16 v[170:171], v242 offset:34048
	ds_read_b64_tr_b16 v[172:173], v242 offset:42240
	v_mfma_f32_16x16x32_bf16 v[102:105], v[174:177], v[134:137], v[102:105]
	v_mfma_f32_16x16x32_bf16 v[110:113], v[174:177], v[150:153], v[110:113]
	ds_read_b64_tr_b16 v[174:175], v242 offset:50432
	ds_read_b64_tr_b16 v[176:177], v242 offset:58624
	s_waitcnt lgkmcnt(4)
	v_mfma_f32_16x16x32_bf16 v[82:85], v[162:165], v[130:133], v[82:85]
	v_mfma_f32_16x16x32_bf16 v[90:93], v[162:165], v[146:149], v[90:93]
	ds_read_b64_tr_b16 v[162:163], v242 offset:34304
	ds_read_b64_tr_b16 v[164:165], v242 offset:42496
	v_mfma_f32_16x16x32_bf16 v[82:85], v[166:169], v[134:137], v[82:85]
	v_mfma_f32_16x16x32_bf16 v[90:93], v[166:169], v[150:153], v[90:93]
	ds_read_b64_tr_b16 v[166:167], v242 offset:50688
	ds_read_b64_tr_b16 v[168:169], v242 offset:58880
	s_waitcnt lgkmcnt(4)
	v_mfma_f32_16x16x32_bf16 v[86:89], v[170:173], v[130:133], v[86:89]
	v_mfma_f32_16x16x32_bf16 v[94:97], v[170:173], v[146:149], v[94:97]
	ds_read_b64_tr_b16 v[170:171], v242 offset:34560
	ds_read_b64_tr_b16 v[172:173], v242 offset:42752
	v_mfma_f32_16x16x32_bf16 v[86:89], v[174:177], v[134:137], v[86:89]
	v_mfma_f32_16x16x32_bf16 v[94:97], v[174:177], v[150:153], v[94:97]
	ds_read_b64_tr_b16 v[174:175], v242 offset:50944
	ds_read_b64_tr_b16 v[176:177], v242 offset:59136
	s_waitcnt lgkmcnt(4)
	v_mfma_f32_16x16x32_bf16 v[66:69], v[162:165], v[130:133], v[66:69]
	v_mfma_f32_16x16x32_bf16 v[74:77], v[162:165], v[146:149], v[74:77]
	ds_read_b64_tr_b16 v[162:163], v242 offset:34816
	ds_read_b64_tr_b16 v[164:165], v242 offset:43008
	v_mfma_f32_16x16x32_bf16 v[66:69], v[166:169], v[134:137], v[66:69]
	v_mfma_f32_16x16x32_bf16 v[74:77], v[166:169], v[150:153], v[74:77]
	ds_read_b64_tr_b16 v[166:167], v242 offset:51200
	ds_read_b64_tr_b16 v[168:169], v242 offset:59392
	s_waitcnt lgkmcnt(4)
	v_mfma_f32_16x16x32_bf16 v[70:73], v[170:173], v[130:133], v[70:73]
	v_mfma_f32_16x16x32_bf16 v[78:81], v[170:173], v[146:149], v[78:81]
	ds_read_b64_tr_b16 v[170:171], v242 offset:35072
	ds_read_b64_tr_b16 v[172:173], v242 offset:43264
	v_mfma_f32_16x16x32_bf16 v[70:73], v[174:177], v[134:137], v[70:73]
	v_mfma_f32_16x16x32_bf16 v[78:81], v[174:177], v[150:153], v[78:81]
	ds_read_b64_tr_b16 v[174:175], v242 offset:51456
	ds_read_b64_tr_b16 v[176:177], v242 offset:59648
	s_waitcnt lgkmcnt(4)
	v_mfma_f32_16x16x32_bf16 v[50:53], v[162:165], v[130:133], v[50:53]
	v_mfma_f32_16x16x32_bf16 v[58:61], v[162:165], v[146:149], v[58:61]
	ds_read_b64_tr_b16 v[162:163], v242 offset:35328
	ds_read_b64_tr_b16 v[164:165], v242 offset:43520
	v_mfma_f32_16x16x32_bf16 v[50:53], v[166:169], v[134:137], v[50:53]
	v_mfma_f32_16x16x32_bf16 v[58:61], v[166:169], v[150:153], v[58:61]
	ds_read_b64_tr_b16 v[166:167], v242 offset:51712
	ds_read_b64_tr_b16 v[168:169], v242 offset:59904
	s_waitcnt lgkmcnt(4)
	v_mfma_f32_16x16x32_bf16 v[54:57], v[170:173], v[130:133], v[54:57]
	v_mfma_f32_16x16x32_bf16 v[62:65], v[170:173], v[146:149], v[62:65]
	ds_read_b64_tr_b16 v[170:171], v242 offset:35584
	ds_read_b64_tr_b16 v[172:173], v242 offset:43776
	v_mfma_f32_16x16x32_bf16 v[54:57], v[174:177], v[134:137], v[54:57]
	v_mfma_f32_16x16x32_bf16 v[62:65], v[174:177], v[150:153], v[62:65]
	ds_read_b64_tr_b16 v[174:175], v242 offset:51968
	ds_read_b64_tr_b16 v[176:177], v242 offset:60160
	s_waitcnt lgkmcnt(4)
	v_mfma_f32_16x16x32_bf16 v[34:37], v[162:165], v[130:133], v[34:37]
	v_mfma_f32_16x16x32_bf16 v[42:45], v[162:165], v[146:149], v[42:45]
	ds_read_b64_tr_b16 v[162:163], v242 offset:35840
	ds_read_b64_tr_b16 v[164:165], v242 offset:44032
	v_mfma_f32_16x16x32_bf16 v[34:37], v[166:169], v[134:137], v[34:37]
	v_mfma_f32_16x16x32_bf16 v[42:45], v[166:169], v[150:153], v[42:45]
	ds_read_b64_tr_b16 v[166:167], v242 offset:52224
	ds_read_b64_tr_b16 v[168:169], v242 offset:60416
	s_waitcnt lgkmcnt(4)
	v_mfma_f32_16x16x32_bf16 v[38:41], v[170:173], v[130:133], v[38:41]
	v_mfma_f32_16x16x32_bf16 v[46:49], v[170:173], v[146:149], v[46:49]
	ds_read_b64_tr_b16 v[170:171], v242 offset:36096
	ds_read_b64_tr_b16 v[172:173], v242 offset:44288
	v_mfma_f32_16x16x32_bf16 v[38:41], v[174:177], v[134:137], v[38:41]
	v_mfma_f32_16x16x32_bf16 v[46:49], v[174:177], v[150:153], v[46:49]
	ds_read_b64_tr_b16 v[174:175], v242 offset:52480
	ds_read_b64_tr_b16 v[176:177], v242 offset:60672
	s_waitcnt lgkmcnt(4)
	v_mfma_f32_16x16x32_bf16 v[18:21], v[162:165], v[130:133], v[18:21]
	v_mfma_f32_16x16x32_bf16 v[26:29], v[162:165], v[146:149], v[26:29]
	ds_read_b64_tr_b16 v[162:163], v242 offset:36352
	ds_read_b64_tr_b16 v[164:165], v242 offset:44544
	v_mfma_f32_16x16x32_bf16 v[18:21], v[166:169], v[134:137], v[18:21]
	v_mfma_f32_16x16x32_bf16 v[26:29], v[166:169], v[150:153], v[26:29]
	ds_read_b64_tr_b16 v[166:167], v242 offset:52736
	ds_read_b64_tr_b16 v[168:169], v242 offset:60928
	s_waitcnt lgkmcnt(4)
	v_mfma_f32_16x16x32_bf16 v[22:25], v[170:173], v[130:133], v[22:25]
	v_mfma_f32_16x16x32_bf16 v[30:33], v[170:173], v[146:149], v[30:33]
	ds_read_b64_tr_b16 v[170:171], v242 offset:36608
	ds_read_b64_tr_b16 v[172:173], v242 offset:44800
	v_mfma_f32_16x16x32_bf16 v[22:25], v[174:177], v[134:137], v[22:25]
	v_mfma_f32_16x16x32_bf16 v[30:33], v[174:177], v[150:153], v[30:33]
	ds_read_b64_tr_b16 v[174:175], v242 offset:52992
	ds_read_b64_tr_b16 v[176:177], v242 offset:61184
	s_waitcnt lgkmcnt(4)
	v_mfma_f32_16x16x32_bf16 v[2:5], v[162:165], v[130:133], v[2:5]
	v_mfma_f32_16x16x32_bf16 v[10:13], v[162:165], v[146:149], v[10:13]
	v_mfma_f32_16x16x32_bf16 v[2:5], v[166:169], v[134:137], v[2:5]
	v_mfma_f32_16x16x32_bf16 v[10:13], v[166:169], v[150:153], v[10:13]
	s_waitcnt lgkmcnt(0)
	v_mfma_f32_16x16x32_bf16 v[6:9], v[170:173], v[130:133], v[6:9]
	v_mfma_f32_16x16x32_bf16 v[14:17], v[170:173], v[146:149], v[14:17]
	v_mfma_f32_16x16x32_bf16 v[6:9], v[174:177], v[134:137], v[6:9]
	v_mfma_f32_16x16x32_bf16 v[14:17], v[174:177], v[150:153], v[14:17]
	s_branch .Lat_end_c
.Lat_redo_c:
	s_mov_b32 s84, 1
	s_waitcnt lgkmcnt(0)
	v_mov_b32_e32 v234, v221
	v_xor_b32_e32 v235, 64, v234
	v_xor_b32_e32 v236, 0x80, v234
	v_xor_b32_e32 v237, 0xc0, v234
	ds_read_b128 v[162:165], v234 offset:32768
	s_waitcnt lgkmcnt(0)
	v_mfma_f32_16x16x32_bf16 v[130:133], v[162:165], v[178:181], v[246:249]
	v_mfma_f32_16x16x32_bf16 v[146:149], v[162:165], v[194:197], v[250:253]
	ds_read_b128 v[162:165], v235 offset:32768
	s_waitcnt lgkmcnt(0)
	v_mfma_f32_16x16x32_bf16 v[130:133], v[162:165], v[182:185], v[130:133]
	v_mfma_f32_16x16x32_bf16 v[146:149], v[162:165], v[198:201], v[146:149]
	ds_read_b128 v[162:165], v236 offset:32768
	s_waitcnt lgkmcnt(0)
	v_mfma_f32_16x16x32_bf16 v[130:133], v[162:165], v[186:189], v[130:133]
	v_mfma_f32_16x16x32_bf16 v[146:149], v[162:165], v[202:205], v[146:149]
	ds_read_b128 v[162:165], v237 offset:32768
	s_waitcnt lgkmcnt(0)
	v_mfma_f32_16x16x32_bf16 v[130:133], v[162:165], v[190:193], v[130:133]
	v_mfma_f32_16x16x32_bf16 v[146:149], v[162:165], v[206:209], v[146:149]
	ds_read_b128 v[162:165], v234 offset:36864
	s_waitcnt lgkmcnt(0)
	v_mfma_f32_16x16x32_bf16 v[134:137], v[162:165], v[178:181], v[246:249]
	v_mfma_f32_16x16x32_bf16 v[150:153], v[162:165], v[194:197], v[250:253]
	ds_read_b128 v[162:165], v235 offset:36864
	s_waitcnt lgkmcnt(0)
	v_mfma_f32_16x16x32_bf16 v[134:137], v[162:165], v[182:185], v[134:137]
	v_mfma_f32_16x16x32_bf16 v[150:153], v[162:165], v[198:201], v[150:153]
	ds_read_b128 v[162:165], v236 offset:36864
	s_waitcnt lgkmcnt(0)
	v_mfma_f32_16x16x32_bf16 v[134:137], v[162:165], v[186:189], v[134:137]
	v_mfma_f32_16x16x32_bf16 v[150:153], v[162:165], v[202:205], v[150:153]
	ds_read_b128 v[162:165], v237 offset:36864
	s_waitcnt lgkmcnt(0)
	v_mfma_f32_16x16x32_bf16 v[134:137], v[162:165], v[190:193], v[134:137]
	v_mfma_f32_16x16x32_bf16 v[150:153], v[162:165], v[206:209], v[150:153]
	ds_read_b128 v[162:165], v234 offset:40960
	s_waitcnt lgkmcnt(0)
	v_mfma_f32_16x16x32_bf16 v[138:141], v[162:165], v[178:181], v[246:249]
	v_mfma_f32_16x16x32_bf16 v[154:157], v[162:165], v[194:197], v[250:253]
	ds_read_b128 v[162:165], v235 offset:40960
	s_waitcnt lgkmcnt(0)
	v_mfma_f32_16x16x32_bf16 v[138:141], v[162:165], v[182:185], v[138:141]
	v_mfma_f32_16x16x32_bf16 v[154:157], v[162:165], v[198:201], v[154:157]
	ds_read_b128 v[162:165], v236 offset:40960
	s_waitcnt lgkmcnt(0)
	v_mfma_f32_16x16x32_bf16 v[138:141], v[162:165], v[186:189], v[138:141]
	v_mfma_f32_16x16x32_bf16 v[154:157], v[162:165], v[202:205], v[154:157]
	ds_read_b128 v[162:165], v237 offset:40960
	s_waitcnt lgkmcnt(0)
	v_mfma_f32_16x16x32_bf16 v[138:141], v[162:165], v[190:193], v[138:141]
	v_mfma_f32_16x16x32_bf16 v[154:157], v[162:165], v[206:209], v[154:157]
	ds_read_b128 v[162:165], v234 offset:45056
	s_waitcnt lgkmcnt(0)
	v_mfma_f32_16x16x32_bf16 v[142:145], v[162:165], v[178:181], v[246:249]
	v_mfma_f32_16x16x32_bf16 v[158:161], v[162:165], v[194:197], v[250:253]
	ds_read_b128 v[162:165], v235 offset:45056
	s_waitcnt lgkmcnt(0)
	v_mfma_f32_16x16x32_bf16 v[142:145], v[162:165], v[182:185], v[142:145]
	v_mfma_f32_16x16x32_bf16 v[158:161], v[162:165], v[198:201], v[158:161]
	ds_read_b128 v[162:165], v236 offset:45056
	s_waitcnt lgkmcnt(0)
	v_mfma_f32_16x16x32_bf16 v[142:145], v[162:165], v[186:189], v[142:145]
	v_mfma_f32_16x16x32_bf16 v[158:161], v[162:165], v[202:205], v[158:161]
	ds_read_b128 v[162:165], v237 offset:45056
	s_waitcnt lgkmcnt(0)
	v_mfma_f32_16x16x32_bf16 v[142:145], v[162:165], v[190:193], v[142:145]
	v_mfma_f32_16x16x32_bf16 v[158:161], v[162:165], v[206:209], v[158:161]
	ds_read_b64_tr_b16 v[162:163], v242 offset:32768
	ds_read_b64_tr_b16 v[164:165], v242 offset:40960
	ds_read_b64_tr_b16 v[166:167], v242 offset:49152
	ds_read_b64_tr_b16 v[168:169], v242 offset:57344
	ds_read_b64_tr_b16 v[170:171], v242 offset:33024
	ds_read_b64_tr_b16 v[172:173], v242 offset:41216
	ds_read_b64_tr_b16 v[174:175], v242 offset:49408
	ds_read_b64_tr_b16 v[176:177], v242 offset:57600
	s_nop 7
	s_branch .Lat_dt_c

.Lat_end_c:
.Lat_next1:
	s_add_i32 s58, s58, 1
	v_add_u32_e32 v223, 0xffffffc0, v223
	s_addk_i32 s91, 0x40
	s_add_u32 s50, s50, 0x80000
	s_addc_u32 s51, s51, 0
	s_mov_b32 s94, 0
	s_branch .Lat_loop
.Lat_final:
	s_waitcnt vmcnt(0) lgkmcnt(0)
	s_barrier
	s_cmp_gt_u32 s58, s89
	s_cbranch_scc1 .Lat_done
	ds_read_b128 v[162:165], v234 offset:32768
	ds_read_b128 v[166:169], v235 offset:32768
	ds_read_b128 v[170:173], v236 offset:32768
	ds_read_b128 v[174:177], v237 offset:32768
	s_waitcnt lgkmcnt(2)
	v_mfma_f32_16x16x32_bf16 v[130:133], v[162:165], v[178:181], v[246:249]
	v_mfma_f32_16x16x32_bf16 v[146:149], v[162:165], v[194:197], v[250:253]
	ds_read_b128 v[162:165], v234 offset:36864
	v_mfma_f32_16x16x32_bf16 v[130:133], v[166:169], v[182:185], v[130:133]
	v_mfma_f32_16x16x32_bf16 v[146:149], v[166:169], v[198:201], v[146:149]
	ds_read_b128 v[166:169], v235 offset:36864
	s_waitcnt lgkmcnt(2)
	v_mfma_f32_16x16x32_bf16 v[130:133], v[170:173], v[186:189], v[130:133]
	v_mfma_f32_16x16x32_bf16 v[146:149], v[170:173], v[202:205], v[146:149]
	ds_read_b128 v[170:173], v236 offset:36864
	v_mfma_f32_16x16x32_bf16 v[130:133], v[174:177], v[190:193], v[130:133]
	v_mfma_f32_16x16x32_bf16 v[146:149], v[174:177], v[206:209], v[146:149]
	ds_read_b128 v[174:177], v237 offset:36864
	s_waitcnt lgkmcnt(2)
	v_mfma_f32_16x16x32_bf16 v[134:137], v[162:165], v[178:181], v[246:249]
	v_mfma_f32_16x16x32_bf16 v[150:153], v[162:165], v[194:197], v[250:253]
	ds_read_b128 v[162:165], v234 offset:40960
	v_mfma_f32_16x16x32_bf16 v[134:137], v[166:169], v[182:185], v[134:137]
	v_mfma_f32_16x16x32_bf16 v[150:153], v[166:169], v[198:201], v[150:153]
	ds_read_b128 v[166:169], v235 offset:40960
	s_waitcnt lgkmcnt(2)
	v_mfma_f32_16x16x32_bf16 v[134:137], v[170:173], v[186:189], v[134:137]
	v_mfma_f32_16x16x32_bf16 v[150:153], v[170:173], v[202:205], v[150:153]
	ds_read_b128 v[170:173], v236 offset:40960
	v_mfma_f32_16x16x32_bf16 v[134:137], v[174:177], v[190:193], v[134:137]
	v_mfma_f32_16x16x32_bf16 v[150:153], v[174:177], v[206:209], v[150:153]
	ds_read_b128 v[174:177], v237 offset:40960
	s_waitcnt lgkmcnt(2)
	v_mfma_f32_16x16x32_bf16 v[138:141], v[162:165], v[178:181], v[246:249]
	v_mfma_f32_16x16x32_bf16 v[154:157], v[162:165], v[194:197], v[250:253]
	ds_read_b128 v[162:165], v234 offset:45056
	v_mfma_f32_16x16x32_bf16 v[138:141], v[166:169], v[182:185], v[138:141]
	v_mfma_f32_16x16x32_bf16 v[154:157], v[166:169], v[198:201], v[154:157]
	ds_read_b128 v[166:169], v235 offset:45056
	s_waitcnt lgkmcnt(2)
	v_mfma_f32_16x16x32_bf16 v[138:141], v[170:173], v[186:189], v[138:141]
	v_mfma_f32_16x16x32_bf16 v[154:157], v[170:173], v[202:205], v[154:157]
	ds_read_b128 v[170:173], v236 offset:45056
	v_mfma_f32_16x16x32_bf16 v[138:141], v[174:177], v[190:193], v[138:141]
	v_mfma_f32_16x16x32_bf16 v[154:157], v[174:177], v[206:209], v[154:157]
	ds_read_b128 v[174:177], v237 offset:45056
	s_waitcnt lgkmcnt(2)
	v_mfma_f32_16x16x32_bf16 v[142:145], v[162:165], v[178:181], v[246:249]
	v_mfma_f32_16x16x32_bf16 v[158:161], v[162:165], v[194:197], v[250:253]
	ds_read_b64_tr_b16 v[162:163], v242 offset:32768
	ds_read_b64_tr_b16 v[164:165], v242 offset:40960
	v_mfma_f32_16x16x32_bf16 v[142:145], v[166:169], v[182:185], v[142:145]
	v_mfma_f32_16x16x32_bf16 v[158:161], v[166:169], v[198:201], v[158:161]
	ds_read_b64_tr_b16 v[166:167], v242 offset:49152
	ds_read_b64_tr_b16 v[168:169], v242 offset:57344
	s_waitcnt lgkmcnt(4)
	v_mfma_f32_16x16x32_bf16 v[142:145], v[170:173], v[186:189], v[142:145]
	v_mfma_f32_16x16x32_bf16 v[158:161], v[170:173], v[202:205], v[158:161]
	ds_read_b64_tr_b16 v[170:171], v242 offset:33024
	ds_read_b64_tr_b16 v[172:173], v242 offset:41216
	v_mfma_f32_16x16x32_bf16 v[142:145], v[174:177], v[190:193], v[142:145]
	v_mfma_f32_16x16x32_bf16 v[158:161], v[174:177], v[206:209], v[158:161]
	ds_read_b64_tr_b16 v[174:175], v242 offset:49408
	ds_read_b64_tr_b16 v[176:177], v242 offset:57600

.Lat_inactive1:
	s_add_i32 m0, s97, 0x0
	s_nop 0
	global_load_lds_dwordx4 v231, s[50:51]
	s_add_i32 m0, s97, 0x400
	s_nop 0
	global_load_lds_dwordx4 v229, s[50:51]
	s_add_i32 m0, s97, 0x800
	s_nop 0
	global_load_lds_dwordx4 v227, s[50:51]
	s_add_i32 m0, s97, 0xc00
	s_nop 0
	global_load_lds_dwordx4 v225, s[50:51]
	s_add_i32 m0, s97, 0x1000
	s_nop 0
	global_load_lds_dwordx4 v230, s[50:51]
	s_add_i32 m0, s97, 0x1400
	s_nop 0
	global_load_lds_dwordx4 v228, s[50:51]
	s_add_i32 m0, s97, 0x1800
	s_nop 0
	global_load_lds_dwordx4 v226, s[50:51]
	s_add_i32 m0, s97, 0x1c00
	s_nop 0
	global_load_lds_dwordx4 v224, s[50:51]
	s_branch .Lat_next1
